# S5 pass 2: next iteration's z-gate loads issued right after the current values are unpacked (before the Y stores); in-loop wait is vmcnt(4) so it no longer waits for store acks
# baseline (speedup 1.0000x reference)
; #define LAS __attribute__((address_space(3)))
; #define MFMA16(A, B, Cc) __builtin_amdgcn_mfma_f32_16x16x32_bf16((A), (B), (Cc), 0, 0, 0)
; #define MFMA16K16(A, B, Cc) __builtin_amdgcn_mfma_f32_16x16x16bf16_1k(__builtin_bit_cast(bf16x4, (A)), __builtin_bit_cast(bf16x4, (B)), (Cc), 0, 0, 0)
; __device__ __forceinline__ unsigned pk2(float lo, float hi) { return pg8::cvt_pk_bf16(lo, hi); }
; __device__ __forceinline__ float bf_lo(unsigned w) { return __uint_as_float(w << 16); }
; __device__ __forceinline__ float bf_hi(unsigned w) { return __uint_as_float(w & 0xffff0000u); }
; __device__ __forceinline__ bf16x8 pack8(f32x4 lo, f32x4 hi) { v4u w; w.x = pk2(lo[0], lo[1]); w.y = pk2(lo[2], lo[3]); w.z = pk2(hi[0], hi[1]); w.w = pk2(hi[2], hi[3]); return __builtin_bit_cast(bf16x8, w); }
; #define S5_UPDATE(K, hre, him, xq) do { const v2u xb_ = (xq); \
;     _Pragma("unroll") for (int j = 0; j < 4; ++j) { const f32x4 cre_ = K.ar[j] * hre[j] - K.ai[j] * him[j], cim_ = K.ar[j] * him[j] + K.ai[j] * hre[j]; \
;         hre[j] = MFMA16K16(K.Bf[2 * j], xb_, cre_); him[j] = MFMA16K16(K.Bf[2 * j + 1], xb_, cim_); } } while (0)
; __device__ __forceinline__ unsigned s5_output(const S5C& K, const f32x4 (&hre)[4], const f32x4 (&him)[4], v2u xq, v2u zq) {
;     f32x4 y = (f32x4){0.f, 0.f, 0.f, 0.f};
; #pragma unroll
;     for (int j = 0; j < 4; ++j) y = MFMA16(K.Cf[j], pack8(hre[j], him[j]), y);
;     const f32x4 xf = (f32x4){bf_lo(xq.x), bf_hi(xq.x), bf_lo(xq.y), bf_hi(xq.y)};
;     y = y + K.dsk * xf;
;     const v2u yb = (v2u){pk2(y[0], y[1]), pk2(y[2], y[3])};
;     const f32x4 gv = MFMA16K16(K.Wv, yb, K.bv), gg = MFMA16K16(K.Wg, yb, K.bg);
; __device__ __forceinline__ void s5_prompt_task(const Args& a, const Ctx& C, int b, int g, v4u (&xv)[8]) {
;     ...
; #pragma unroll 1
;     for (int t0 = 0; t0 < 16; t0 += 4) {
; #pragma unroll
;         for (int u = 0; u < 4; ++u) { const int t = t0 + u, tok = 16 * chunk + t;
;             const v2u xq = *(const LAS v2u*)(xsl + t * 32);
;             S5_UPDATE(K, hre, him, xq);
;             *(unsigned*)((unsigned char*)Y + (row0 + tok) * DM + DA + g * 16 + 4 * q) = s5_output(K, hre, him, xq, zq[u]);
;             const size_t tn = row0 + ((t + 4 < 16) ? tok + 4 : tok);
;             zq[u] = __builtin_nontemporal_load((const v2u*)(ZBg + (size_t)(tn - row0) * 16 + 4 * q)); } }
.LBB0_988:
	ds_read2_b64 v[78:81], v163 offset1:4
	v_mov_b32_e32 v119, v5
	v_mov_b32_e32 v3, v4
	v_pk_mul_f32 v[150:151], v[88:89], v[46:47]
	v_mov_b32_e32 v121, v9
	v_mov_b32_e32 v123, v13
	v_pk_mul_f32 v[142:143], v[118:119], v[48:49]
	v_pk_mul_f32 v[148:149], v[88:89], v[62:63]
	v_mov_b32_e32 v7, v8
	v_pk_mul_f32 v[154:155], v[92:93], v[54:55]
	v_mov_b32_e32 v11, v12
	v_pk_mul_f32 v[158:159], v[96:97], v[38:39]
	v_mov_b32_e32 v125, v17
	v_add_co_u32_e32 v112, vcc, s2, v106
	v_pk_mul_f32 v[140:141], v[118:119], v[64:65]
	v_pk_fma_f32 v[62:63], v[86:87], v[62:63], v[150:151]
	v_pk_mul_f32 v[146:147], v[120:121], v[56:57]
	v_pk_mul_f32 v[150:151], v[122:123], v[40:41]
	v_pk_fma_f32 v[64:65], v[2:3], v[64:65], v[142:143]
	v_pk_mul_f32 v[152:153], v[92:93], v[66:67]
	v_pk_mul_f32 v[156:157], v[96:97], v[70:71]
	v_mov_b32_e32 v15, v16
	v_pk_mul_f32 v[164:165], v[100:101], v[58:59]
	v_add_u32_e32 v108, s0, v110
	v_addc_co_u32_e32 v113, vcc, -1, v107, vcc
	s_cmp_lt_u32 s0, 12
	v_pk_fma_f32 v[46:47], v[86:87], v[46:47], v[148:149] neg_lo:[0,0,1] neg_hi:[0,0,1]
	v_pk_mul_f32 v[144:145], v[120:121], v[68:69]
	v_pk_fma_f32 v[66:67], v[90:91], v[66:67], v[154:155]
	v_pk_mul_f32 v[148:149], v[122:123], v[72:73]
	v_pk_fma_f32 v[70:71], v[94:95], v[70:71], v[158:159]
	v_pk_mul_f32 v[154:155], v[124:125], v[60:61]
	v_pk_fma_f32 v[48:49], v[2:3], v[48:49], v[140:141] neg_lo:[0,0,1] neg_hi:[0,0,1]
	s_waitcnt lgkmcnt(0)
	v_mfma_f32_16x16x16_bf16 v[62:65], v[116:117], v[78:79], v[62:65]
	v_fma_f32 v68, v6, v68, v146
	v_fma_f32 v69, v7, v69, v147
	v_pk_fma_f32 v[72:73], v[10:11], v[72:73], v[150:151]
	v_pk_mul_f32 v[160:161], v[100:101], v[74:75]
	v_pk_fma_f32 v[54:55], v[90:91], v[54:55], v[152:153] neg_lo:[0,0,1] neg_hi:[0,0,1]
	v_pk_fma_f32 v[38:39], v[94:95], v[38:39], v[156:157] neg_lo:[0,0,1] neg_hi:[0,0,1]
	v_pk_mul_f32 v[152:153], v[124:125], v[76:77]
	v_pk_fma_f32 v[74:75], v[98:99], v[74:75], v[164:165]
	v_mfma_f32_16x16x16_bf16 v[46:49], v[114:115], v[78:79], v[46:49]
	v_add_u32_e32 v140, 4, v108
	s_cselect_b64 vcc, -1, 0
	v_pk_fma_f32 v[40:41], v[10:11], v[40:41], v[148:149] neg_lo:[0,0,1] neg_hi:[0,0,1]
	v_mfma_f32_16x16x16_bf16 v[66:69], v[128:129], v[78:79], v[66:69]
	v_fma_f32 v76, v14, v76, v154
	v_fma_f32 v77, v15, v77, v155
	v_pk_fma_f32 v[58:59], v[98:99], v[58:59], v[160:161] neg_lo:[0,0,1] neg_hi:[0,0,1]
	v_add_u32_e32 v142, 1, v108
	v_mfma_f32_16x16x16_bf16 v[70:73], v[132:133], v[78:79], v[70:73]
	v_add_u32_e32 v143, 5, v108
	v_pk_fma_f32 v[56:57], v[6:7], v[56:57], v[144:145] neg_lo:[0,0,1] neg_hi:[0,0,1]
	v_add_u32_e32 v144, 2, v108
	v_add_u32_e32 v145, 6, v108
	v_add_u32_e32 v156, 3, v108
	v_add_u32_e32 v157, 7, v108
	v_mfma_f32_16x16x16_bf16 v[38:41], v[130:131], v[78:79], v[38:41]
	v_fma_f32 v60, v14, v60, -v152
	v_fma_f32 v61, v15, v61, -v153
	v_cndmask_b32_e32 v108, v108, v140, vcc
	v_lshlrev_b64 v[140:141], 5, v[108:109]
	v_mfma_f32_16x16x16_bf16 v[74:77], v[136:137], v[78:79], v[74:77]
	v_cndmask_b32_e32 v108, v142, v143, vcc
	v_lshl_add_u64 v[142:143], v[138:139], 0, v[140:141]
	v_lshlrev_b64 v[140:141], 5, v[108:109]
	v_mfma_f32_16x16x16_bf16 v[58:61], v[134:135], v[78:79], v[58:61]
	v_cndmask_b32_e32 v108, v144, v145, vcc
	v_pk_mul_f32 v[184:185], v[118:119], v[64:65]
	v_lshlrev_b32_e32 v164, 16, v78
	v_mfma_f32_16x16x16_bf16 v[54:57], v[126:127], v[78:79], v[54:57]
	v_and_b32_e32 v165, 0xffff0000, v78
	v_lshlrev_b32_e32 v206, 16, v79
	v_and_b32_e32 v207, 0xffff0000, v79
	v_lshl_add_u64 v[78:79], v[138:139], 0, v[140:141]
	v_lshlrev_b64 v[140:141], 5, v[108:109]
	v_cndmask_b32_e32 v108, v156, v157, vcc
	v_cvt_pk_bf16_f32 v157, v68, v69
	v_pk_mul_f32 v[186:187], v[88:89], v[62:63]
	v_pk_mul_f32 v[188:189], v[2:3], v[64:65]
	v_pk_mul_f32 v[190:191], v[86:87], v[62:63]
	v_pk_mul_f32 v[192:193], v[120:121], v[68:69]
	v_pk_mul_f32 v[196:197], v[6:7], v[68:69]
	v_pk_fma_f32 v[68:69], v[2:3], v[48:49], v[184:185] neg_lo:[0,0,1] neg_hi:[0,0,1]
	v_pk_mul_f32 v[184:185], v[96:97], v[70:71]
	v_cvt_pk_bf16_f32 v150, v46, v47
	v_cvt_pk_bf16_f32 v151, v48, v49
	v_cvt_pk_bf16_f32 v156, v66, v67
	v_cvt_pk_bf16_f32 v160, v70, v71
	v_pk_mul_f32 v[194:195], v[92:93], v[66:67]
	v_pk_mul_f32 v[198:199], v[90:91], v[66:67]
	v_pk_mul_f32 v[200:201], v[122:123], v[72:73]
	v_pk_fma_f32 v[66:67], v[86:87], v[46:47], v[186:187] neg_lo:[0,0,1] neg_hi:[0,0,1]
	v_pk_fma_f32 v[48:49], v[118:119], v[48:49], v[188:189]
	v_pk_fma_f32 v[46:47], v[88:89], v[46:47], v[190:191]
	v_pk_mul_f32 v[186:187], v[10:11], v[72:73]
	v_pk_mul_f32 v[188:189], v[94:95], v[70:71]
	v_pk_mul_f32 v[190:191], v[124:125], v[76:77]
	v_pk_fma_f32 v[70:71], v[94:95], v[38:39], v[184:185] neg_lo:[0,0,1] neg_hi:[0,0,1]
	v_pk_mul_f32 v[184:185], v[100:101], v[74:75]
	v_cvt_pk_bf16_f32 v152, v62, v63
	v_cvt_pk_bf16_f32 v153, v64, v65
	v_cvt_pk_bf16_f32 v159, v40, v41
	v_cvt_pk_bf16_f32 v161, v72, v73
	v_pk_fma_f32 v[72:73], v[10:11], v[40:41], v[200:201] neg_lo:[0,0,1] neg_hi:[0,0,1]
	v_pk_fma_f32 v[40:41], v[122:123], v[40:41], v[186:187]
	v_pk_fma_f32 v[186:187], v[14:15], v[60:61], v[190:191] neg_lo:[0,0,1] neg_hi:[0,0,1]
	v_pk_fma_f32 v[184:185], v[98:99], v[58:59], v[184:185] neg_lo:[0,0,1] neg_hi:[0,0,1]
	v_cvt_pk_bf16_f32 v154, v54, v55
	v_cvt_pk_bf16_f32 v155, v56, v57
	v_cvt_pk_bf16_f32 v158, v38, v39
	v_mfma_f32_16x16x32_bf16 v[62:65], v[30:33], v[150:153], 0
	v_fma_f32 v152, v6, v56, -v192
	v_fma_f32 v153, v7, v57, -v193
	v_pk_fma_f32 v[150:151], v[90:91], v[54:55], v[194:195] neg_lo:[0,0,1] neg_hi:[0,0,1]
	v_pk_fma_f32 v[56:57], v[120:121], v[56:57], v[196:197]
	v_pk_fma_f32 v[54:55], v[92:93], v[54:55], v[198:199]
	v_pk_fma_f32 v[38:39], v[96:97], v[38:39], v[188:189]
; #define LAS __attribute__((address_space(3)))
; #define MFMA16(A, B, Cc) __builtin_amdgcn_mfma_f32_16x16x32_bf16((A), (B), (Cc), 0, 0, 0)
; #define MFMA16K16(A, B, Cc) __builtin_amdgcn_mfma_f32_16x16x16bf16_1k(__builtin_bit_cast(bf16x4, (A)), __builtin_bit_cast(bf16x4, (B)), (Cc), 0, 0, 0)
; __device__ __forceinline__ unsigned pk2(float lo, float hi) { return pg8::cvt_pk_bf16(lo, hi); }
; __device__ __forceinline__ float bf_lo(unsigned w) { return __uint_as_float(w << 16); }
; __device__ __forceinline__ float bf_hi(unsigned w) { return __uint_as_float(w & 0xffff0000u); }
; __device__ __forceinline__ bf16x8 pack8(f32x4 lo, f32x4 hi) { v4u w; w.x = pk2(lo[0], lo[1]); w.y = pk2(lo[2], lo[3]); w.z = pk2(hi[0], hi[1]); w.w = pk2(hi[2], hi[3]); return __builtin_bit_cast(bf16x8, w); }
; #define S5_UPDATE(K, hre, him, xq) do { const v2u xb_ = (xq); \
;     _Pragma("unroll") for (int j = 0; j < 4; ++j) { const f32x4 cre_ = K.ar[j] * hre[j] - K.ai[j] * him[j], cim_ = K.ar[j] * him[j] + K.ai[j] * hre[j]; \
;         hre[j] = MFMA16K16(K.Bf[2 * j], xb_, cre_); him[j] = MFMA16K16(K.Bf[2 * j + 1], xb_, cim_); } } while (0)
; __device__ __forceinline__ unsigned s5_output(const S5C& K, const f32x4 (&hre)[4], const f32x4 (&him)[4], v2u xq, v2u zq) {
;     f32x4 y = (f32x4){0.f, 0.f, 0.f, 0.f};
; #pragma unroll
;     for (int j = 0; j < 4; ++j) y = MFMA16(K.Cf[j], pack8(hre[j], him[j]), y);
;     const f32x4 xf = (f32x4){bf_lo(xq.x), bf_hi(xq.x), bf_lo(xq.y), bf_hi(xq.y)};
;     y = y + K.dsk * xf;
;     const v2u yb = (v2u){pk2(y[0], y[1]), pk2(y[2], y[3])};
;     const f32x4 gv = MFMA16K16(K.Wv, yb, K.bv), gg = MFMA16K16(K.Wg, yb, K.bg);
; __device__ __forceinline__ void s5_prompt_task(const Args& a, const Ctx& C, int b, int g, v4u (&xv)[8]) {
;     ...
; #pragma unroll 1
;     for (int t0 = 0; t0 < 16; t0 += 4) {
; #pragma unroll
;         for (int u = 0; u < 4; ++u) { const int t = t0 + u, tok = 16 * chunk + t;
;             const v2u xq = *(const LAS v2u*)(xsl + t * 32);
;             S5_UPDATE(K, hre, him, xq);
;             *(unsigned*)((unsigned char*)Y + (row0 + tok) * DM + DA + g * 16 + 4 * q) = s5_output(K, hre, him, xq, zq[u]);
;             const size_t tn = row0 + ((t + 4 < 16) ? tok + 4 : tok);
;             zq[u] = __builtin_nontemporal_load((const v2u*)(ZBg + (size_t)(tn - row0) * 16 + 4 * q)); } }
	v_pk_mul_f32 v[192:193], v[14:15], v[76:77]
	v_mfma_f32_16x16x16_bf16 v[186:189], v[134:135], v[80:81], v[184:187]
	v_fma_f32 v192, v124, v60, v192
	v_fma_f32 v193, v125, v61, v193
	ds_read2_b64 v[82:85], v163 offset0:8 offset1:12
	v_cvt_pk_bf16_f32 v182, v58, v59
	v_pk_mul_f32 v[184:185], v[98:99], v[74:75]
	v_mfma_f32_16x16x16_bf16 v[66:69], v[114:115], v[80:81], v[66:69]
	v_fma_f32 v190, v100, v58, v184
	v_fma_f32 v191, v101, v59, v185
	v_cvt_pk_bf16_f32 v183, v60, v61
	v_cvt_pk_bf16_f32 v185, v76, v77
	v_mfma_f32_16x16x16_bf16 v[46:49], v[116:117], v[80:81], v[46:49]
	v_lshlrev_b32_e32 v208, 16, v80
	v_and_b32_e32 v209, 0xffff0000, v80
	v_cvt_pk_bf16_f32 v184, v74, v75
	v_mfma_f32_16x16x16_bf16 v[54:57], v[128:129], v[80:81], v[54:57]
	v_lshlrev_b32_e32 v210, 16, v81
	s_nop 2
	v_pk_mul_f32 v[194:195], v[2:3], v[48:49]
	v_pk_mul_f32 v[196:197], v[86:87], v[46:47]
	v_mfma_f32_16x16x16_bf16 v[150:153], v[126:127], v[80:81], v[150:153]
	v_and_b32_e32 v211, 0xffff0000, v81
	v_pk_mul_f32 v[198:199], v[120:121], v[56:57]
	v_cvt_pk_bf16_f32 v77, v56, v57
	v_mfma_f32_16x16x16_bf16 v[38:41], v[132:133], v[80:81], v[38:41]
	v_mul_f32_e64 v200, v92, v54
	v_mul_f32_e64 v201, v93, v55
	v_pk_mul_f32 v[202:203], v[6:7], v[56:57]
	s_nop 0
	v_cvt_pk_bf16_f32 v75, v152, v153
	v_mfma_f32_16x16x16_bf16 v[190:193], v[136:137], v[80:81], v[190:193]
	v_cvt_pk_bf16_f32 v76, v54, v55
	v_pk_mul_f32 v[204:205], v[90:91], v[54:55]
	v_pk_mul_f32 v[216:217], v[122:123], v[40:41]
	v_mfma_f32_16x16x16_bf16 v[70:73], v[130:131], v[80:81], v[70:73]
	v_cvt_pk_bf16_f32 v74, v150, v151
	s_waitcnt lgkmcnt(0)
	v_lshlrev_b32_e32 v212, 16, v82
	v_and_b32_e32 v213, 0xffff0000, v82
	v_mfma_f32_16x16x32_bf16 v[58:61], v[50:53], v[154:157], v[62:65]
	v_mul_f32_e64 v154, v118, v48
	v_mul_f32_e64 v155, v119, v49
	v_pk_mul_f32 v[156:157], v[88:89], v[46:47]
	v_pk_fma_f32 v[56:57], v[2:3], v[68:69], v[154:155] neg_lo:[0,0,1] neg_hi:[0,0,1]
	v_cvt_pk_bf16_f32 v62, v66, v67
	v_cvt_pk_bf16_f32 v63, v68, v69
	v_cvt_pk_bf16_f32 v64, v46, v47
	v_cvt_pk_bf16_f32 v65, v48, v49
	v_pk_mul_f32 v[154:155], v[96:97], v[38:39]
	v_cvt_pk_bf16_f32 v80, v70, v71
	v_mfma_f32_16x16x32_bf16 v[46:49], v[30:33], v[62:65], 0
	v_fma_f32 v64, v118, v68, v194
	v_fma_f32 v65, v119, v69, v195
	v_pk_fma_f32 v[62:63], v[88:89], v[66:67], v[196:197]
	v_pk_fma_f32 v[68:69], v[6:7], v[152:153], v[198:199] neg_lo:[0,0,1] neg_hi:[0,0,1]
	v_pk_mul_f32 v[196:197], v[94:95], v[38:39]
	v_pk_mul_f32 v[198:199], v[124:125], v[192:193]
	v_pk_fma_f32 v[54:55], v[86:87], v[66:67], v[156:157] neg_lo:[0,0,1] neg_hi:[0,0,1]
	v_pk_mul_f32 v[194:195], v[10:11], v[40:41]
	v_pk_fma_f32 v[66:67], v[90:91], v[150:151], v[200:201] neg_lo:[0,0,1] neg_hi:[0,0,1]
	v_pk_fma_f32 v[152:153], v[120:121], v[152:153], v[202:203]
	v_pk_fma_f32 v[154:155], v[94:95], v[70:71], v[154:155] neg_lo:[0,0,1] neg_hi:[0,0,1]
	v_pk_mul_f32 v[200:201], v[100:101], v[190:191]
	v_pk_fma_f32 v[70:71], v[96:97], v[70:71], v[196:197]
	v_pk_mul_f32 v[202:203], v[14:15], v[192:193]
	v_pk_fma_f32 v[196:197], v[14:15], v[188:189], v[198:199] neg_lo:[0,0,1] neg_hi:[0,0,1]
	v_pk_mul_f32 v[198:199], v[98:99], v[190:191]
	v_cvt_pk_bf16_f32 v81, v72, v73
	v_mfma_f32_16x16x16_bf16 v[62:65], v[116:117], v[82:83], v[62:65]
	v_fma_f32 v150, v92, v150, v204
	v_fma_f32 v151, v93, v151, v205
	v_pk_fma_f32 v[156:157], v[10:11], v[72:73], v[216:217] neg_lo:[0,0,1] neg_hi:[0,0,1]
	v_pk_fma_f32 v[72:73], v[122:123], v[72:73], v[194:195]
	v_pk_fma_f32 v[194:195], v[98:99], v[186:187], v[200:201] neg_lo:[0,0,1] neg_hi:[0,0,1]
	v_pk_fma_f32 v[200:201], v[124:125], v[188:189], v[202:203]
	v_pk_fma_f32 v[198:199], v[100:101], v[186:187], v[198:199]
	v_lshlrev_b32_e32 v214, 16, v83
	v_and_b32_e32 v215, 0xffff0000, v83
	v_mfma_f32_16x16x16_bf16 v[54:57], v[114:115], v[82:83], v[54:57]
	v_cvt_pk_bf16_f32 v186, v186, v187
	v_cvt_pk_bf16_f32 v187, v188, v189
	v_cvt_pk_bf16_f32 v189, v192, v193
	v_mfma_f32_16x16x16_bf16 v[66:69], v[126:127], v[82:83], v[66:69]
	v_cvt_pk_bf16_f32 v188, v190, v191
	v_lshlrev_b32_e32 v144, 16, v84
	v_and_b32_e32 v145, 0xffff0000, v84
	v_mfma_f32_16x16x16_bf16 v[150:153], v[128:129], v[82:83], v[150:153]
	v_lshlrev_b32_e32 v146, 16, v85
	s_nop 2
	v_cvt_pk_bf16_f32 v190, v66, v67
	v_cvt_pk_bf16_f32 v191, v68, v69
	v_mfma_f32_16x16x16_bf16 v[154:157], v[130:131], v[82:83], v[154:157]
	v_and_b32_e32 v147, 0xffff0000, v85
	v_cvt_pk_bf16_f32 v192, v150, v151
	v_cvt_pk_bf16_f32 v193, v152, v153
	v_mfma_f32_16x16x16_bf16 v[70:73], v[132:133], v[82:83], v[70:73]
	v_mul_f32_e64 v216, v6, v152
	v_mul_f32_e64 v217, v7, v153
	v_pk_mul_f32 v[218:219], v[90:91], v[150:151]
	s_nop 0
	v_cvt_pk_bf16_f32 v202, v154, v155
	v_mfma_f32_16x16x16_bf16 v[194:197], v[134:135], v[82:83], v[194:197]
	v_cvt_pk_bf16_f32 v203, v156, v157
	s_nop 0
	v_cvt_pk_bf16_f32 v204, v70, v71
	v_cvt_pk_bf16_f32 v205, v72, v73
	v_mfma_f32_16x16x16_bf16 v[198:201], v[136:137], v[82:83], v[198:201]
	v_cvt_pk_bf16_f32 v82, v38, v39
	v_cvt_pk_bf16_f32 v83, v40, v41
	v_pk_mul_f32 v[220:221], v[122:123], v[72:73]
	v_mfma_f32_16x16x32_bf16 v[38:41], v[42:45], v[158:161], v[58:61]
	v_lshlrev_b64 v[148:149], 5, v[108:109]
	v_mov_b32_e32 v166, 0
	v_mov_b32_e32 v171, v109
	v_pk_mul_f32 v[58:59], v[118:119], v[64:65]
	v_pk_mul_f32 v[60:61], v[88:89], v[62:63]
	v_mfma_f32_16x16x32_bf16 v[158:161], v[50:53], v[74:77], v[46:49]
	v_mul_f32_e64 v74, v120, v152
	v_mul_f32_e64 v75, v121, v153
	v_pk_mul_f32 v[76:77], v[92:93], v[150:151]
	v_mov_b32_e32 v176, v109
	v_cvt_pk_bf16_f32 v46, v54, v55
	v_cvt_pk_bf16_f32 v47, v56, v57
	v_cvt_pk_bf16_f32 v48, v62, v63
	v_cvt_pk_bf16_f32 v49, v64, v65
	v_pk_mul_f32 v[64:65], v[2:3], v[64:65]
; #define MFMA16(A, B, Cc) __builtin_amdgcn_mfma_f32_16x16x32_bf16((A), (B), (Cc), 0, 0, 0)
; #define MFMA16K16(A, B, Cc) __builtin_amdgcn_mfma_f32_16x16x16bf16_1k(__builtin_bit_cast(bf16x4, (A)), __builtin_bit_cast(bf16x4, (B)), (Cc), 0, 0, 0)
; __device__ __forceinline__ unsigned pk2(float lo, float hi) { return pg8::cvt_pk_bf16(lo, hi); }
; __device__ __forceinline__ float bf_lo(unsigned w) { return __uint_as_float(w << 16); }
; __device__ __forceinline__ unsigned pk4f8(float a, float b, float c, float d) { int p = __builtin_amdgcn_cvt_pk_fp8_f32(sat8(a), sat8(b), 0, false); p = __builtin_amdgcn_cvt_pk_fp8_f32(sat8(c), sat8(d), p, true); return (unsigned)p; }
; __device__ __forceinline__ float bf_hi(unsigned w) { return __uint_as_float(w & 0xffff0000u); }
; __device__ __forceinline__ bf16x8 pack8(f32x4 lo, f32x4 hi) { v4u w; w.x = pk2(lo[0], lo[1]); w.y = pk2(lo[2], lo[3]); w.z = pk2(hi[0], hi[1]); w.w = pk2(hi[2], hi[3]); return __builtin_bit_cast(bf16x8, w); }
; __device__ __forceinline__ unsigned s5_output(const S5C& K, const f32x4 (&hre)[4], const f32x4 (&him)[4], v2u xq, v2u zq) {
;     f32x4 y = (f32x4){0.f, 0.f, 0.f, 0.f};
; #pragma unroll
;     for (int j = 0; j < 4; ++j) y = MFMA16(K.Cf[j], pack8(hre[j], him[j]), y);
;     const f32x4 xf = (f32x4){bf_lo(xq.x), bf_hi(xq.x), bf_lo(xq.y), bf_hi(xq.y)};
;     y = y + K.dsk * xf;
;     const v2u yb = (v2u){pk2(y[0], y[1]), pk2(y[2], y[3])};
;     const f32x4 gv = MFMA16K16(K.Wv, yb, K.bv), gg = MFMA16K16(K.Wg, yb, K.bg);
;     const f32x4 zf = (f32x4){bf_lo(zq.x), bf_hi(zq.x), bf_lo(zq.y), bf_hi(zq.y)};
;     f32x4 o;
; #pragma unroll
;     for (int r = 0; r < 4; ++r) o[r] = gv[r] * __builtin_amdgcn_rcpf(1.0f + __expf(-gg[r])) * zf[r];
;     return pk4f8(o[0], o[1], o[2], o[3]);
	v_pk_mul_f32 v[62:63], v[86:87], v[62:63]
	v_mfma_f32_16x16x32_bf16 v[182:185], v[34:37], v[182:185], v[38:41]
	v_mov_b32_e32 v225, v109
	v_lshl_add_u64 v[140:141], v[138:139], 0, v[140:141]
	v_lshl_add_u64 v[148:149], v[138:139], 0, v[148:149]
	v_pk_fma_f32 v[40:41], v[2:3], v[56:57], v[58:59] neg_lo:[0,0,1] neg_hi:[0,0,1]
	v_pk_fma_f32 v[38:39], v[86:87], v[54:55], v[60:61] neg_lo:[0,0,1] neg_hi:[0,0,1]
	v_mfma_f32_16x16x32_bf16 v[150:153], v[30:33], v[46:49], 0
	v_mul_f32_e64 v58, v96, v70
	v_mul_f32_e64 v59, v97, v71
	v_pk_mul_f32 v[60:61], v[10:11], v[72:73]
	v_pk_mul_f32 v[70:71], v[94:95], v[70:71]
	v_mfma_f32_16x16x16_bf16 v[46:49], v[114:115], v[84:85], v[38:41]
	v_fma_f32 v60, v122, v156, v60
	v_fma_f32 v61, v123, v157, v61
	v_add_u32_e32 v163, 0x80, v163
	s_add_i32 s0, s0, 4
	v_pk_fma_f32 v[40:41], v[118:119], v[56:57], v[64:65]
	v_pk_fma_f32 v[38:39], v[88:89], v[54:55], v[62:63]
	v_mfma_f32_16x16x32_bf16 v[80:83], v[42:45], v[80:83], v[158:161]
	s_and_b64 vcc, exec, vcc
	v_mfma_f32_16x16x16_bf16 v[62:65], v[116:117], v[84:85], v[38:41]
	s_nop 0
	v_fma_f32 v158, v18, v164, v182
	v_fma_f32 v159, v19, v165, v183
	v_cvt_pk_bf16_f32 v164, v158, v159
	v_pk_fma_f32 v[40:41], v[6:7], v[68:69], v[74:75] neg_lo:[0,0,1] neg_hi:[0,0,1]
	v_pk_fma_f32 v[38:39], v[90:91], v[66:67], v[76:77] neg_lo:[0,0,1] neg_hi:[0,0,1]
	v_pk_mul_f32 v[74:75], v[124:125], v[200:201]
	v_pk_mul_f32 v[76:77], v[100:101], v[198:199]
	v_mfma_f32_16x16x16_bf16 v[54:57], v[126:127], v[84:85], v[38:41]
	v_cvt_pk_bf16_f32 v158, v46, v47
	v_cvt_pk_bf16_f32 v159, v48, v49
	v_cvt_pk_bf16_f32 v160, v62, v63
	v_pk_fma_f32 v[40:41], v[120:121], v[68:69], v[216:217]
	v_pk_fma_f32 v[38:39], v[92:93], v[66:67], v[218:219]
	v_mfma_f32_16x16x32_bf16 v[150:153], v[50:53], v[190:193], v[150:153]
	v_cvt_pk_bf16_f32 v161, v64, v65
	v_mfma_f32_16x16x16_bf16 v[66:69], v[128:129], v[84:85], v[38:41]
	s_nop 2
	v_fma_f32 v38, v94, v154, -v58
	v_fma_f32 v39, v95, v155, -v59
	v_pk_fma_f32 v[58:59], v[96:97], v[154:155], v[70:71]
	v_pk_mul_f32 v[154:155], v[14:15], v[200:201]
	v_pk_fma_f32 v[40:41], v[10:11], v[156:157], v[220:221] neg_lo:[0,0,1] neg_hi:[0,0,1]
	v_mfma_f32_16x16x16_bf16 v[70:73], v[132:133], v[84:85], v[58:61]
	v_cvt_pk_bf16_f32 v156, v198, v199
	v_cvt_pk_bf16_f32 v157, v200, v201
	s_nop 0
	v_pk_fma_f32 v[60:61], v[14:15], v[196:197], v[74:75] neg_lo:[0,0,1] neg_hi:[0,0,1]
	v_pk_mul_f32 v[74:75], v[98:99], v[198:199]
	v_pk_fma_f32 v[58:59], v[98:99], v[194:195], v[76:77] neg_lo:[0,0,1] neg_hi:[0,0,1]
	v_pk_fma_f32 v[76:77], v[124:125], v[196:197], v[154:155]
	v_pk_fma_f32 v[74:75], v[100:101], v[194:195], v[74:75]
	v_mfma_f32_16x16x16_bf16 v[38:41], v[130:131], v[84:85], v[38:41]
	v_cvt_pk_bf16_f32 v154, v194, v195
	v_cvt_pk_bf16_f32 v155, v196, v197
	v_cvt_pk_bf16_f32 v194, v54, v55
	v_mfma_f32_16x16x16_bf16 v[58:61], v[134:135], v[84:85], v[58:61]
	v_cvt_pk_bf16_f32 v195, v56, v57
	v_cvt_pk_bf16_f32 v196, v66, v67
	v_cvt_pk_bf16_f32 v197, v68, v69
	v_mfma_f32_16x16x16_bf16 v[74:77], v[136:137], v[84:85], v[74:77]
	v_fma_f32 v84, v20, v206, v184
	v_fma_f32 v85, v21, v207, v185
	s_nop 1
	v_cvt_pk_bf16_f32 v198, v58, v59
	v_cvt_pk_bf16_f32 v165, v84, v85
	v_mfma_f32_16x16x32_bf16 v[80:83], v[34:37], v[186:189], v[80:83]
	v_cvt_pk_bf16_f32 v186, v38, v39
	v_cvt_pk_bf16_f32 v187, v40, v41
	v_cvt_pk_bf16_f32 v188, v70, v71
	v_mfma_f32_16x16x16_bf16 v[190:193], v[104:105], v[164:165], v[26:29]
	v_cvt_pk_bf16_f32 v189, v72, v73
	s_nop 2
	v_pk_fma_f32 v[80:81], v[18:19], v[208:209], v[80:81]
	v_cvt_pk_bf16_f32 v199, v60, v61
	v_mfma_f32_16x16x32_bf16 v[158:161], v[30:33], v[158:161], 0
	v_cvt_pk_bf16_f32 v80, v80, v81
	v_mul_f32_e32 v3, 0xbfb8aa3b, v190
	v_mul_f32_e32 v7, 0xbfb8aa3b, v191
	v_mfma_f32_16x16x32_bf16 v[150:153], v[42:45], v[202:205], v[150:153]
	v_exp_f32_e32 v3, v3
	v_exp_f32_e32 v7, v7
	v_mul_f32_e32 v11, 0xbfb8aa3b, v192
	v_mfma_f32_16x16x16_bf16 v[182:185], v[102:103], v[164:165], v[22:25]
	v_fma_f32 v164, v20, v210, v82
	v_fma_f32 v165, v21, v211, v83
	v_mul_f32_e32 v15, 0xbfb8aa3b, v193
	v_cvt_pk_bf16_f32 v81, v164, v165
	v_mfma_f32_16x16x32_bf16 v[82:85], v[50:53], v[194:197], v[158:161]
	v_exp_f32_e32 v11, v11
	v_exp_f32_e32 v15, v15
	v_add_f32_e32 v3, 1.0, v3
	v_mfma_f32_16x16x32_bf16 v[150:153], v[34:37], v[154:157], v[150:153]
	v_add_f32_e32 v7, 1.0, v7
	v_rcp_f32_e32 v3, v3
	v_rcp_f32_e32 v7, v7
	v_mfma_f32_16x16x16_bf16 v[194:197], v[104:105], v[80:81], v[26:29]
	v_cvt_pk_bf16_f32 v200, v74, v75
	s_nop 2
	v_pk_fma_f32 v[150:151], v[18:19], v[212:213], v[150:151]
	v_cvt_pk_bf16_f32 v201, v76, v77
	v_mfma_f32_16x16x16_bf16 v[158:161], v[102:103], v[80:81], v[22:25]
	v_cvt_pk_bf16_f32 v154, v150, v151
	v_mul_f32_e32 v108, 0xbfb8aa3b, v194
	v_mul_f32_e32 v119, 0xbfb8aa3b, v195
	v_mfma_f32_16x16x32_bf16 v[80:83], v[42:45], v[186:189], v[82:85]
	v_exp_f32_e32 v108, v108
	v_exp_f32_e32 v119, v119
	v_add_f32_e32 v11, 1.0, v11
	v_pk_fma_f32 v[84:85], v[20:21], v[214:215], v[152:153]
	v_mfma_f32_16x16x32_bf16 v[80:83], v[34:37], v[198:201], v[80:83]
	v_cvt_pk_bf16_f32 v155, v84, v85
	v_mul_f32_e32 v84, 0xbfb8aa3b, v196
	v_mul_f32_e32 v85, 0xbfb8aa3b, v197
	v_exp_f32_e32 v84, v84
	v_mfma_f32_16x16x16_bf16 v[150:153], v[102:103], v[154:155], v[22:25]
	v_exp_f32_e32 v85, v85
	v_add_f32_e32 v15, 1.0, v15
	v_rcp_f32_e32 v11, v11
	v_mfma_f32_16x16x16_bf16 v[154:157], v[104:105], v[154:155], v[26:29]
	v_rcp_f32_e32 v15, v15
	v_mul_f32_e32 v3, v182, v3
	v_mul_f32_e32 v7, v183, v7
	s_waitcnt vmcnt(4)
; #define LAS __attribute__((address_space(3)))
; #define MFMA16K16(A, B, Cc) __builtin_amdgcn_mfma_f32_16x16x16bf16_1k(__builtin_bit_cast(bf16x4, (A)), __builtin_bit_cast(bf16x4, (B)), (Cc), 0, 0, 0)
; __device__ __forceinline__ float bf_lo(unsigned w) { return __uint_as_float(w << 16); }
; __device__ __forceinline__ unsigned pk4f8(float a, float b, float c, float d) { int p = __builtin_amdgcn_cvt_pk_fp8_f32(sat8(a), sat8(b), 0, false); p = __builtin_amdgcn_cvt_pk_fp8_f32(sat8(c), sat8(d), p, true); return (unsigned)p; }
; __device__ __forceinline__ float bf_hi(unsigned w) { return __uint_as_float(w & 0xffff0000u); }
; #define S5_UPDATE(K, hre, him, xq) do { const v2u xb_ = (xq); \
;     _Pragma("unroll") for (int j = 0; j < 4; ++j) { const f32x4 cre_ = K.ar[j] * hre[j] - K.ai[j] * him[j], cim_ = K.ar[j] * him[j] + K.ai[j] * hre[j]; \
;         hre[j] = MFMA16K16(K.Bf[2 * j], xb_, cre_); him[j] = MFMA16K16(K.Bf[2 * j + 1], xb_, cim_); } } while (0)
; __device__ __forceinline__ unsigned s5_output(const S5C& K, const f32x4 (&hre)[4], const f32x4 (&him)[4], v2u xq, v2u zq) {
;     ...
;     const f32x4 gv = MFMA16K16(K.Wv, yb, K.bv), gg = MFMA16K16(K.Wg, yb, K.bg);
;     const f32x4 zf = (f32x4){bf_lo(zq.x), bf_hi(zq.x), bf_lo(zq.y), bf_hi(zq.y)};
;     f32x4 o;
; #pragma unroll
;     for (int r = 0; r < 4; ++r) o[r] = gv[r] * __builtin_amdgcn_rcpf(1.0f + __expf(-gg[r])) * zf[r];
;     return pk4f8(o[0], o[1], o[2], o[3]);
; __device__ __forceinline__ void s5_prompt_task(const Args& a, const Ctx& C, int b, int g, v4u (&xv)[8]) {
;     ...
;         for (int u = 0; u < 4; ++u) { const int t = t0 + u, tok = 16 * chunk + t;
;             const v2u xq = *(const LAS v2u*)(xsl + t * 32);
;             S5_UPDATE(K, hre, him, xq);
;             *(unsigned*)((unsigned char*)Y + (row0 + tok) * DM + DA + g * 16 + 4 * q) = s5_output(K, hre, him, xq, zq[u]);
;             const size_t tn = row0 + ((t + 4 < 16) ? tok + 4 : tok);
;             zq[u] = __builtin_nontemporal_load((const v2u*)(ZBg + (size_t)(tn - row0) * 16 + 4 * q)); } }
	v_lshlrev_b32_e32 v177, 16, v230
	v_and_b32_e32 v178, 0xffff0000, v230
	v_lshlrev_b32_e32 v179, 16, v231
	v_and_b32_e32 v180, 0xffff0000, v231
	v_lshlrev_b32_e32 v167, 16, v226
	v_and_b32_e32 v168, 0xffff0000, v226
	v_lshlrev_b32_e32 v169, 16, v227
	v_and_b32_e32 v170, 0xffff0000, v227
	v_lshlrev_b32_e32 v181, 16, v232
	v_and_b32_e32 v222, 0xffff0000, v232
	v_lshlrev_b32_e32 v223, 16, v233
	v_and_b32_e32 v224, 0xffff0000, v233
	v_lshlrev_b32_e32 v172, 16, v228
	v_and_b32_e32 v173, 0xffff0000, v228
	v_lshlrev_b32_e32 v174, 16, v229
	v_and_b32_e32 v175, 0xffff0000, v229
	global_load_dwordx2 v[226:227], v[142:143], off nt
	global_load_dwordx2 v[228:229], v[78:79], off nt
	global_load_dwordx2 v[230:231], v[140:141], off nt
	global_load_dwordx2 v[232:233], v[148:149], off nt
	v_mul_f32_e32 v3, v3, v167
	v_mul_f32_e32 v7, v7, v168
	v_add_f32_e32 v108, 1.0, v108
	v_add_f32_e32 v119, 1.0, v119
	v_add_f32_e32 v84, 1.0, v84
	v_add_f32_e32 v85, 1.0, v85
	v_med3_f32 v3, v3, s1, v111
	v_med3_f32 v7, v7, s1, v111
	v_rcp_f32_e32 v108, v108
	v_rcp_f32_e32 v119, v119
	v_rcp_f32_e32 v121, v84
	v_mul_f32_e32 v84, 0xbfb8aa3b, v154
	v_pk_fma_f32 v[82:83], v[20:21], v[146:147], v[82:83]
	v_pk_fma_f32 v[80:81], v[18:19], v[144:145], v[80:81]
	v_rcp_f32_e32 v123, v85
	v_cvt_pk_fp8_f32 v166, v3, v7
	v_exp_f32_e32 v3, v84
	v_cvt_pk_bf16_f32 v84, v80, v81
	v_cvt_pk_bf16_f32 v85, v82, v83
	v_mul_f32_e32 v11, v184, v11
	v_mul_f32_e32 v15, v185, v15
	v_mfma_f32_16x16x16_bf16 v[144:147], v[104:105], v[84:85], v[26:29]
	v_mul_f32_e32 v11, v11, v169
	v_mul_f32_e32 v15, v15, v170
	v_mul_f32_e32 v125, 0xbfb8aa3b, v155
	v_med3_f32 v11, v11, s1, v111
	v_med3_f32 v15, v15, s1, v111
	v_mul_f32_e32 v154, 0xbfb8aa3b, v156
	v_mul_f32_e32 v155, 0xbfb8aa3b, v157
	v_mfma_f32_16x16x16_bf16 v[80:83], v[102:103], v[84:85], v[22:25]
	v_exp_f32_e32 v7, v125
	v_mul_f32_e32 v84, v158, v108
	v_mul_f32_e32 v85, v159, v119
	v_exp_f32_e32 v125, v154
	v_exp_f32_e32 v154, v155
	v_cvt_pk_fp8_f32 v166, v11, v15 op_sel:[0,0,1]
	v_mul_f32_e32 v11, v84, v172
	v_mul_f32_e32 v15, v85, v173
	v_mul_f32_e32 v108, v160, v121
	v_mul_f32_e32 v119, v161, v123
	v_med3_f32 v11, v11, s1, v111
	v_med3_f32 v15, v15, s1, v111
	v_mul_f32_e32 v121, 0xbfb8aa3b, v144
	v_mul_f32_e32 v123, 0xbfb8aa3b, v145
	v_cvt_pk_fp8_f32 v171, v11, v15
	v_exp_f32_e32 v11, v121
	v_exp_f32_e32 v15, v123
	v_add_f32_e32 v3, 1.0, v3
	v_add_f32_e32 v7, 1.0, v7
	v_mul_f32_e32 v84, v108, v174
	v_mul_f32_e32 v85, v119, v175
	v_add_f32_e32 v108, 1.0, v125
	v_add_f32_e32 v119, 1.0, v154
	v_rcp_f32_e32 v3, v3
	v_rcp_f32_e32 v7, v7
	v_rcp_f32_e32 v108, v108
	v_rcp_f32_e32 v119, v119
	v_mul_f32_e32 v125, 0xbfb8aa3b, v146
	v_mul_f32_e32 v144, 0xbfb8aa3b, v147
	v_exp_f32_e32 v121, v125
	v_exp_f32_e32 v123, v144
	v_add_f32_e32 v11, 1.0, v11
	v_add_f32_e32 v15, 1.0, v15
	v_rcp_f32_e32 v11, v11
	v_rcp_f32_e32 v15, v15
	v_mul_f32_e32 v3, v150, v3
	v_mul_f32_e32 v7, v151, v7
	v_med3_f32 v84, v84, s1, v111
	v_med3_f32 v85, v85, s1, v111
	global_store_dword v[112:113], v166, off offset:-2048
	v_mul_f32_e32 v108, v152, v108
	v_mul_f32_e32 v112, v153, v119
	v_mul_f32_e32 v3, v3, v177
	v_mul_f32_e32 v7, v7, v178
	v_cvt_pk_fp8_f32 v171, v84, v85 op_sel:[0,0,1]
	v_mul_f32_e32 v84, v108, v179
	v_mul_f32_e32 v85, v112, v180
	v_add_f32_e32 v108, 1.0, v121
	v_add_f32_e32 v112, 1.0, v123
	v_med3_f32 v3, v3, s1, v111
	v_med3_f32 v7, v7, s1, v111
	v_rcp_f32_e32 v108, v108
	v_rcp_f32_e32 v112, v112
	v_cvt_pk_fp8_f32 v176, v3, v7
	v_mul_f32_e32 v3, v80, v11
	v_mul_f32_e32 v7, v81, v15
	v_mul_f32_e32 v3, v3, v181
	v_mul_f32_e32 v7, v7, v222
	v_med3_f32 v3, v3, s1, v111
	v_med3_f32 v7, v7, s1, v111
	v_cvt_pk_fp8_f32 v225, v3, v7
	v_mul_f32_e32 v11, v82, v108
	v_mul_f32_e32 v15, v83, v112
	v_med3_f32 v84, v84, s1, v111
	v_med3_f32 v85, v85, s1, v111
	v_mul_f32_e32 v11, v11, v223
	v_mul_f32_e32 v3, v15, v224
	v_cvt_pk_fp8_f32 v176, v84, v85 op_sel:[0,0,1]
	v_med3_f32 v7, v11, s1, v111
	v_med3_f32 v3, v3, s1, v111
	v_cvt_pk_fp8_f32 v225, v7, v3 op_sel:[0,0,1]
	s_nop 0
	global_store_dword v[106:107], v171, off offset:-4096
	s_nop 0
	global_store_dword v[106:107], v176, off offset:-2048
	s_nop 0
	global_store_dword v[106:107], v225, off
	v_lshl_add_u64 v[106:107], v[106:107], 0, s[4:5]
	s_cbranch_vccnz .LBB0_988
